# GEMM loop: hipcc per-block s_setprio 1/0 flips removed, one static s_setprio 1 for waves 4-7 per tile (reset after the GEMM phase)
# speedup vs baseline: 1.0108x; 1.0108x over previous
; #define PG8_STAGE(bufoff, gbase, voff) do { _Pragma("unroll") for (int _i = 0; _i < 2; ++_i) \
;         __builtin_amdgcn_global_load_lds((const unsigned*)((const char*)(gbase) + (voff)[_i]), (LAS unsigned*)(lds + (bufoff) + ldsw + _i * 8192), 16, 0, 0); } while (0)
; #define PG8_LDA(dst, b, h) do { _Pragma("unroll") for (int m = 0; m < 4; ++m) _Pragma("unroll") for (int k = 0; k < 2; ++k) dst[m][k] = *(const LAS bf16x8*)(lds + PG8_SA(b, h) + aoff + m * 2048 + k * 1024); } while (0)
; #define PG8_LDB(dst, b, h) do { _Pragma("unroll") for (int n = 0; n < 2; ++n) _Pragma("unroll") for (int k = 0; k < 2; ++k) dst[n][k] = *(const LAS bf16x8*)(lds + PG8_SB(b, h) + boff + n * 2048 + k * 1024); } while (0)
; #define PG8_MMA(ai, bj, At, Bt) do { __builtin_amdgcn_s_setprio(1); _Pragma("unroll") for (int m = 0; m < 4; ++m) _Pragma("unroll") for (int n = 0; n < 2; ++n) _Pragma("unroll") for (int k = 0; k < 2; ++k) \
;         acc[ai][bj][m][n] = __builtin_amdgcn_mfma_f32_16x16x32_bf16(Bt[n][k], At[m][k], acc[ai][bj][m][n], 0, 0, 0); __builtin_amdgcn_s_setprio(0); } while (0)
; #define PG8_WAIT_V(n) asm volatile("s_waitcnt vmcnt(" #n ")" ::: "memory")
; #define PG8_WAIT_L(n) asm volatile("s_waitcnt lgkmcnt(" #n ")" ::: "memory")
; #define PG8_BAR __builtin_amdgcn_s_barrier()
; __device__ __forceinline__ void gemm_phase(LAS unsigned char* lds, const Params& p, const Sched& S, float alpha, const int TIDX) {
;     ...
;         for (int t = 0; t < nt; t += 2) {
;             const bool last = (t == nt - 2);
;             const char* a1 = cA + (size_t)(t + 1) * kstep;
;             const char* a2 = last ? nA : cA + (size_t)(t + 2) * kstep; const char* b2 = last ? nB : cB + (size_t)(t + 2) * kstep;
;             const char* a3 = a2 + kstep; const char* b3 = b2 + kstep;
;             PG8_LDB(B0, 0, 0); PG8_SCHED; PG8_LDA(At, 0, 0); PG8_STAGE(PG8_SA(1, 1), a1 + hstep, voffA);
;             PG8_WAIT_L(8); PG8_BAR; PG8_WAIT_L(0); PG8_MMA(0, 0, At, B0); PG8_BAR; PG8_SCHED;
;             PG8_LDB(B1, 0, 1); PG8_STAGE(PG8_SB(0, 0), b2, voffB);
;             PG8_BAR; PG8_WAIT_L(0); PG8_MMA(0, 1, At, B1); PG8_BAR;
;             PG8_LDA(At, 0, 1); PG8_STAGE(PG8_SA(0, 0), a2, voffA);
;             PG8_BAR; PG8_WAIT_L(0); PG8_MMA(1, 0, At, B0); PG8_BAR; PG8_SCHED;
;             PG8_STAGE(PG8_SB(0, 1), b2 + hstep, voffB);
;             PG8_WAIT_V(6); PG8_BAR; PG8_MMA(1, 1, At, B1); PG8_BAR;
.LBB0_287:
	s_cmp_lt_i32 s79, 1
	s_cbranch_scc1 .LBB0_290
	s_add_i32 s38, s79, -2
	s_add_u32 s6, s58, 0x80
	s_addc_u32 s7, s59, 0
	s_add_u32 s39, s60, 0x100
	s_addc_u32 s56, s61, 0
	s_mov_b32 s48, 0
	v_readlane_b32 s74, v254, 3
	s_nop 3
	s_cmp_ge_u32 s74, 4
	s_cbranch_scc0 .Lgemm_prio_done
	s_setprio 1
.Lgemm_prio_done:
	s_add_i32 s57, s48, 2
	s_add_u32 s50, s6, 0x80
	s_addc_u32 s49, s7, 0
	s_add_i32 s74, 0, 0x10000
	v_add_u32_e32 v0, s74, v200
	ds_read_b128 v[130:133], v0
	ds_read_b128 v[134:137], v0 offset:1024
	ds_read_b128 v[154:157], v0 offset:2048
	ds_read_b128 v[158:161], v0 offset:3072
	s_cmp_eq_u32 s38, s48
	s_cselect_b32 s48, s44, s50
	s_cselect_b32 s49, s45, s49
	s_cselect_b32 s51, s47, s56
	s_cselect_b32 s50, s46, s39
	v_lshl_add_u64 v[166:167], s[6:7], 0, v[150:151]
	s_add_i32 m0, s35, 0xc000
	ds_read_b128 v[162:165], v202
	ds_read_b128 v[170:173], v202 offset:1024
	ds_read_b128 v[174:177], v202 offset:2048
	ds_read_b128 v[178:181], v202 offset:3072
	ds_read_b128 v[182:185], v202 offset:4096
	ds_read_b128 v[204:207], v202 offset:5120
	ds_read_b128 v[208:211], v202 offset:6144
	ds_read_b128 v[212:215], v202 offset:7168
	global_load_lds_dwordx4 v[166:167], off
	v_lshl_add_u64 v[166:167], s[6:7], 0, v[152:153]
	s_add_i32 m0, s35, 0xe000
	s_nop 0
	global_load_lds_dwordx4 v[166:167], off
	s_waitcnt lgkmcnt(8)
	s_barrier
	s_waitcnt lgkmcnt(0)
	s_waitcnt lgkmcnt(0)
	v_mfma_f32_16x16x32_bf16 v[126:129], v[130:133], v[162:165], 0
	v_mfma_f32_16x16x32_bf16 v[118:121], v[154:157], v[162:165], 0
	v_mfma_f32_16x16x32_bf16 v[110:113], v[130:133], v[174:177], 0
	v_mfma_f32_16x16x32_bf16 v[102:105], v[154:157], v[174:177], 0
	v_mfma_f32_16x16x32_bf16 v[94:97], v[130:133], v[182:185], 0
	v_mfma_f32_16x16x32_bf16 v[86:89], v[154:157], v[182:185], 0
	v_mfma_f32_16x16x32_bf16 v[78:81], v[130:133], v[208:211], 0
	v_mfma_f32_16x16x32_bf16 v[70:73], v[154:157], v[208:211], 0
	v_mfma_f32_16x16x32_bf16 v[126:129], v[134:137], v[170:173], v[126:129]
	v_mfma_f32_16x16x32_bf16 v[118:121], v[158:161], v[170:173], v[118:121]
	v_mfma_f32_16x16x32_bf16 v[110:113], v[134:137], v[178:181], v[110:113]
	v_mfma_f32_16x16x32_bf16 v[102:105], v[158:161], v[178:181], v[102:105]
	v_mfma_f32_16x16x32_bf16 v[94:97], v[134:137], v[204:207], v[94:97]
	v_mfma_f32_16x16x32_bf16 v[86:89], v[158:161], v[204:207], v[86:89]
	v_mfma_f32_16x16x32_bf16 v[78:81], v[134:137], v[212:215], v[78:81]
	v_mfma_f32_16x16x32_bf16 v[70:73], v[158:161], v[212:215], v[70:73]
	s_barrier
	s_add_i32 s75, 0, 0x14000
	s_add_i32 s74, s74, s34
	v_add_u32_e32 v0, s75, v200
	v_lshl_add_u64 v[166:167], s[50:51], 0, v[140:141]
	s_mov_b32 m0, s74
	ds_read_b128 v[216:219], v0
	ds_read_b128 v[220:223], v0 offset:1024
	ds_read_b128 v[224:227], v0 offset:2048
	ds_read_b128 v[228:231], v0 offset:3072
	global_load_lds_dwordx4 v[166:167], off
	v_lshl_add_u64 v[186:187], s[50:51], 0, v[144:145]
	s_add_i32 m0, s74, 0x2000
	s_nop 0
	global_load_lds_dwordx4 v[186:187], off
	s_barrier
	s_waitcnt lgkmcnt(0)
	s_waitcnt lgkmcnt(0)
	v_mfma_f32_16x16x32_bf16 v[122:125], v[216:219], v[162:165], 0
	v_mfma_f32_16x16x32_bf16 v[114:117], v[224:227], v[162:165], 0
	v_mfma_f32_16x16x32_bf16 v[106:109], v[216:219], v[174:177], 0
	v_mfma_f32_16x16x32_bf16 v[98:101], v[224:227], v[174:177], 0
	v_mfma_f32_16x16x32_bf16 v[90:93], v[216:219], v[182:185], 0
	v_mfma_f32_16x16x32_bf16 v[82:85], v[224:227], v[182:185], 0
	v_mfma_f32_16x16x32_bf16 v[74:77], v[216:219], v[208:211], 0
	v_mfma_f32_16x16x32_bf16 v[66:69], v[224:227], v[208:211], 0
	v_mfma_f32_16x16x32_bf16 v[122:125], v[220:223], v[170:173], v[122:125]
	v_mfma_f32_16x16x32_bf16 v[114:117], v[228:231], v[170:173], v[114:117]
	v_mfma_f32_16x16x32_bf16 v[106:109], v[220:223], v[178:181], v[106:109]
	v_mfma_f32_16x16x32_bf16 v[98:101], v[228:231], v[178:181], v[98:101]
	v_mfma_f32_16x16x32_bf16 v[90:93], v[220:223], v[204:207], v[90:93]
	v_mfma_f32_16x16x32_bf16 v[82:85], v[228:231], v[204:207], v[82:85]
	v_mfma_f32_16x16x32_bf16 v[74:77], v[220:223], v[212:215], v[74:77]
	v_mfma_f32_16x16x32_bf16 v[66:69], v[228:231], v[212:215], v[66:69]
	s_mov_b32 m0, s35
	v_lshl_add_u64 v[232:233], s[48:49], 0, v[138:139]
	s_barrier
	ds_read_b128 v[162:165], v202 offset:16384
	ds_read_b128 v[170:173], v202 offset:17408
	ds_read_b128 v[174:177], v202 offset:18432
	ds_read_b128 v[178:181], v202 offset:19456
	ds_read_b128 v[182:185], v202 offset:20480
	ds_read_b128 v[204:207], v202 offset:21504
	ds_read_b128 v[208:211], v202 offset:22528
	ds_read_b128 v[212:215], v202 offset:23552
	global_load_lds_dwordx4 v[232:233], off
	v_lshl_add_u64 v[234:235], s[48:49], 0, v[142:143]
	s_mov_b32 m0, s36
	s_nop 0
	global_load_lds_dwordx4 v[234:235], off
	s_barrier
	s_waitcnt lgkmcnt(0)
	s_waitcnt lgkmcnt(0)
	v_mfma_f32_16x16x32_bf16 v[62:65], v[130:133], v[162:165], 0
	v_mfma_f32_16x16x32_bf16 v[54:57], v[154:157], v[162:165], 0
	v_mfma_f32_16x16x32_bf16 v[46:49], v[130:133], v[174:177], 0
	v_mfma_f32_16x16x32_bf16 v[38:41], v[154:157], v[174:177], 0
	v_mfma_f32_16x16x32_bf16 v[30:33], v[130:133], v[182:185], 0
	v_mfma_f32_16x16x32_bf16 v[22:25], v[154:157], v[182:185], 0
	v_mfma_f32_16x16x32_bf16 v[14:17], v[130:133], v[208:211], 0
	v_mfma_f32_16x16x32_bf16 v[6:9], v[154:157], v[208:211], 0
	v_mfma_f32_16x16x32_bf16 v[62:65], v[134:137], v[170:173], v[62:65]
	v_mfma_f32_16x16x32_bf16 v[54:57], v[158:161], v[170:173], v[54:57]
	v_mfma_f32_16x16x32_bf16 v[46:49], v[134:137], v[178:181], v[46:49]
	v_mfma_f32_16x16x32_bf16 v[38:41], v[158:161], v[178:181], v[38:41]
	v_mfma_f32_16x16x32_bf16 v[30:33], v[134:137], v[204:207], v[30:33]
	v_mfma_f32_16x16x32_bf16 v[22:25], v[158:161], v[204:207], v[22:25]
	v_mfma_f32_16x16x32_bf16 v[14:17], v[134:137], v[212:215], v[14:17]
	v_mfma_f32_16x16x32_bf16 v[6:9], v[158:161], v[212:215], v[6:9]
	s_barrier
; #define PG8_STAGE(bufoff, gbase, voff) do { _Pragma("unroll") for (int _i = 0; _i < 2; ++_i) \
;         __builtin_amdgcn_global_load_lds((const unsigned*)((const char*)(gbase) + (voff)[_i]), (LAS unsigned*)(lds + (bufoff) + ldsw + _i * 8192), 16, 0, 0); } while (0)
; #define PG8_LDA(dst, b, h) do { _Pragma("unroll") for (int m = 0; m < 4; ++m) _Pragma("unroll") for (int k = 0; k < 2; ++k) dst[m][k] = *(const LAS bf16x8*)(lds + PG8_SA(b, h) + aoff + m * 2048 + k * 1024); } while (0)
; #define PG8_LDB(dst, b, h) do { _Pragma("unroll") for (int n = 0; n < 2; ++n) _Pragma("unroll") for (int k = 0; k < 2; ++k) dst[n][k] = *(const LAS bf16x8*)(lds + PG8_SB(b, h) + boff + n * 2048 + k * 1024); } while (0)
; #define PG8_MMA(ai, bj, At, Bt) do { __builtin_amdgcn_s_setprio(1); _Pragma("unroll") for (int m = 0; m < 4; ++m) _Pragma("unroll") for (int n = 0; n < 2; ++n) _Pragma("unroll") for (int k = 0; k < 2; ++k) \
;         acc[ai][bj][m][n] = __builtin_amdgcn_mfma_f32_16x16x32_bf16(Bt[n][k], At[m][k], acc[ai][bj][m][n], 0, 0, 0); __builtin_amdgcn_s_setprio(0); } while (0)
; #define PG8_WAIT_V(n) asm volatile("s_waitcnt vmcnt(" #n ")" ::: "memory")
; #define PG8_WAIT_L(n) asm volatile("s_waitcnt lgkmcnt(" #n ")" ::: "memory")
; #define PG8_BAR __builtin_amdgcn_s_barrier()
; #define PG8_SCHED __builtin_amdgcn_sched_barrier(0)
; __device__ __forceinline__ void gemm_phase(LAS unsigned char* lds, const Params& p, const Sched& S, float alpha, const int TIDX) {
;     ...
;             PG8_WAIT_V(6); PG8_BAR; PG8_MMA(1, 1, At, B1); PG8_BAR;
;             PG8_LDB(B0, 1, 0); PG8_SCHED; PG8_LDA(At, 1, 0); PG8_STAGE(PG8_SA(0, 1), a2 + hstep, voffA);
;             PG8_WAIT_L(8); PG8_BAR; PG8_WAIT_L(0); PG8_MMA(0, 0, At, B0); PG8_BAR; PG8_SCHED;
;             PG8_LDB(B1, 1, 1); PG8_STAGE(PG8_SB(1, 0), b3, voffB);
;             PG8_BAR; PG8_WAIT_L(0); PG8_MMA(0, 1, At, B1); PG8_BAR;
;             PG8_LDA(At, 1, 1); PG8_STAGE(PG8_SA(1, 0), a3, voffA);
	s_add_u32 s50, s50, s20
	s_addc_u32 s51, s51, 0
	s_add_i32 s74, s75, s34
	v_lshl_add_u64 v[236:237], s[50:51], 0, v[140:141]
	s_mov_b32 m0, s74
	v_lshl_add_u64 v[238:239], s[50:51], 0, v[144:145]
	global_load_lds_dwordx4 v[236:237], off
	s_add_i32 m0, s74, 0x2000
	s_nop 0
	global_load_lds_dwordx4 v[238:239], off
	s_waitcnt vmcnt(6)
	s_barrier
	v_mfma_f32_16x16x32_bf16 v[58:61], v[216:219], v[162:165], 0
	v_mfma_f32_16x16x32_bf16 v[50:53], v[224:227], v[162:165], 0
	v_mfma_f32_16x16x32_bf16 v[42:45], v[216:219], v[174:177], 0
	v_mfma_f32_16x16x32_bf16 v[34:37], v[224:227], v[174:177], 0
	v_mfma_f32_16x16x32_bf16 v[26:29], v[216:219], v[182:185], 0
	v_mfma_f32_16x16x32_bf16 v[18:21], v[224:227], v[182:185], 0
	v_mfma_f32_16x16x32_bf16 v[10:13], v[216:219], v[208:211], 0
	v_mfma_f32_16x16x32_bf16 v[2:5], v[224:227], v[208:211], 0
	v_mfma_f32_16x16x32_bf16 v[58:61], v[220:223], v[170:173], v[58:61]
	v_mfma_f32_16x16x32_bf16 v[50:53], v[228:231], v[170:173], v[50:53]
	v_mfma_f32_16x16x32_bf16 v[42:45], v[220:223], v[178:181], v[42:45]
	v_mfma_f32_16x16x32_bf16 v[34:37], v[228:231], v[178:181], v[34:37]
	v_mfma_f32_16x16x32_bf16 v[26:29], v[220:223], v[204:207], v[26:29]
	v_mfma_f32_16x16x32_bf16 v[18:21], v[228:231], v[204:207], v[18:21]
	v_mfma_f32_16x16x32_bf16 v[10:13], v[220:223], v[212:215], v[10:13]
	v_mfma_f32_16x16x32_bf16 v[2:5], v[228:231], v[212:215], v[2:5]
	s_add_i32 s50, 0, 0x18000
	v_add_u32_e32 v0, s50, v200
	s_barrier
	ds_read_b128 v[130:133], v0
	ds_read_b128 v[134:137], v0 offset:1024
	ds_read_b128 v[154:157], v0 offset:2048
	ds_read_b128 v[158:161], v0 offset:3072
	s_add_u32 s48, s48, s20
	s_addc_u32 s49, s49, 0
	s_mov_b32 m0, s37
	v_lshl_add_u64 v[216:217], s[48:49], 0, v[138:139]
	ds_read_b128 v[162:165], v202 offset:32768
	ds_read_b128 v[170:173], v202 offset:33792
	ds_read_b128 v[174:177], v202 offset:34816
	ds_read_b128 v[178:181], v202 offset:35840
	ds_read_b128 v[182:185], v202 offset:36864
	ds_read_b128 v[204:207], v202 offset:37888
	ds_read_b128 v[208:211], v202 offset:38912
	ds_read_b128 v[212:215], v202 offset:39936
	global_load_lds_dwordx4 v[216:217], off
	v_lshl_add_u64 v[216:217], s[48:49], 0, v[142:143]
	s_mov_b32 m0, s24
	s_nop 0
	global_load_lds_dwordx4 v[216:217], off
	s_waitcnt lgkmcnt(8)
	s_barrier
	s_waitcnt lgkmcnt(0)
	s_waitcnt lgkmcnt(0)
	v_mfma_f32_16x16x32_bf16 v[126:129], v[130:133], v[162:165], v[126:129]
	v_mfma_f32_16x16x32_bf16 v[118:121], v[154:157], v[162:165], v[118:121]
	v_mfma_f32_16x16x32_bf16 v[110:113], v[130:133], v[174:177], v[110:113]
	v_mfma_f32_16x16x32_bf16 v[102:105], v[154:157], v[174:177], v[102:105]
	v_mfma_f32_16x16x32_bf16 v[94:97], v[130:133], v[182:185], v[94:97]
	v_mfma_f32_16x16x32_bf16 v[86:89], v[154:157], v[182:185], v[86:89]
	v_mfma_f32_16x16x32_bf16 v[78:81], v[130:133], v[208:211], v[78:81]
	v_mfma_f32_16x16x32_bf16 v[70:73], v[154:157], v[208:211], v[70:73]
	v_mfma_f32_16x16x32_bf16 v[126:129], v[134:137], v[170:173], v[126:129]
	v_mfma_f32_16x16x32_bf16 v[118:121], v[158:161], v[170:173], v[118:121]
	v_mfma_f32_16x16x32_bf16 v[110:113], v[134:137], v[178:181], v[110:113]
	v_mfma_f32_16x16x32_bf16 v[102:105], v[158:161], v[178:181], v[102:105]
	v_mfma_f32_16x16x32_bf16 v[94:97], v[134:137], v[204:207], v[94:97]
	v_mfma_f32_16x16x32_bf16 v[86:89], v[158:161], v[204:207], v[86:89]
	v_mfma_f32_16x16x32_bf16 v[78:81], v[134:137], v[212:215], v[78:81]
	v_mfma_f32_16x16x32_bf16 v[70:73], v[158:161], v[212:215], v[70:73]
	s_barrier
	s_add_i32 s48, 0, 0x1c000
	s_add_i32 s49, s50, s34
	v_add_u32_e32 v0, s48, v200
	v_lshl_add_u64 v[166:167], v[166:167], 0, s[88:89]
	s_mov_b32 m0, s49
	ds_read_b128 v[216:219], v0
	ds_read_b128 v[220:223], v0 offset:1024
	ds_read_b128 v[224:227], v0 offset:2048
	ds_read_b128 v[228:231], v0 offset:3072
	global_load_lds_dwordx4 v[166:167], off
	v_lshl_add_u64 v[166:167], v[186:187], 0, s[88:89]
	s_add_i32 m0, s49, 0x2000
	s_nop 0
	global_load_lds_dwordx4 v[166:167], off
	s_barrier
	s_waitcnt lgkmcnt(0)
	s_waitcnt lgkmcnt(0)
	v_mfma_f32_16x16x32_bf16 v[122:125], v[216:219], v[162:165], v[122:125]
	v_mfma_f32_16x16x32_bf16 v[114:117], v[224:227], v[162:165], v[114:117]
	v_mfma_f32_16x16x32_bf16 v[106:109], v[216:219], v[174:177], v[106:109]
	v_mfma_f32_16x16x32_bf16 v[98:101], v[224:227], v[174:177], v[98:101]
	v_mfma_f32_16x16x32_bf16 v[90:93], v[216:219], v[182:185], v[90:93]
	v_mfma_f32_16x16x32_bf16 v[82:85], v[224:227], v[182:185], v[82:85]
	v_mfma_f32_16x16x32_bf16 v[74:77], v[216:219], v[208:211], v[74:77]
	v_mfma_f32_16x16x32_bf16 v[66:69], v[224:227], v[208:211], v[66:69]
	v_mfma_f32_16x16x32_bf16 v[122:125], v[220:223], v[170:173], v[122:125]
	v_mfma_f32_16x16x32_bf16 v[114:117], v[228:231], v[170:173], v[114:117]
	v_mfma_f32_16x16x32_bf16 v[106:109], v[220:223], v[178:181], v[106:109]
	v_mfma_f32_16x16x32_bf16 v[98:101], v[228:231], v[178:181], v[98:101]
	v_mfma_f32_16x16x32_bf16 v[90:93], v[220:223], v[204:207], v[90:93]
	v_mfma_f32_16x16x32_bf16 v[82:85], v[228:231], v[204:207], v[82:85]
	v_mfma_f32_16x16x32_bf16 v[74:77], v[220:223], v[212:215], v[74:77]
	v_mfma_f32_16x16x32_bf16 v[66:69], v[228:231], v[212:215], v[66:69]
	s_mov_b32 m0, s25
	v_lshl_add_u64 v[166:167], v[232:233], 0, s[88:89]
	s_barrier
	ds_read_b128 v[162:165], v202 offset:49152
	ds_read_b128 v[170:173], v202 offset:50176
	ds_read_b128 v[174:177], v202 offset:51200
	ds_read_b128 v[178:181], v202 offset:52224
	ds_read_b128 v[182:185], v202 offset:53248
	ds_read_b128 v[204:207], v202 offset:54272
	ds_read_b128 v[208:211], v202 offset:55296
	ds_read_b128 v[212:215], v202 offset:56320
	global_load_lds_dwordx4 v[166:167], off
	v_lshl_add_u64 v[166:167], v[234:235], 0, s[88:89]
	s_mov_b32 m0, s68
	s_nop 0
	global_load_lds_dwordx4 v[166:167], off
	s_barrier
; #define PG8_STAGE(bufoff, gbase, voff) do { _Pragma("unroll") for (int _i = 0; _i < 2; ++_i) \
;         __builtin_amdgcn_global_load_lds((const unsigned*)((const char*)(gbase) + (voff)[_i]), (LAS unsigned*)(lds + (bufoff) + ldsw + _i * 8192), 16, 0, 0); } while (0)
; #define PG8_LDA(dst, b, h) do { _Pragma("unroll") for (int m = 0; m < 4; ++m) _Pragma("unroll") for (int k = 0; k < 2; ++k) dst[m][k] = *(const LAS bf16x8*)(lds + PG8_SA(b, h) + aoff + m * 2048 + k * 1024); } while (0)
; #define PG8_LDB(dst, b, h) do { _Pragma("unroll") for (int n = 0; n < 2; ++n) _Pragma("unroll") for (int k = 0; k < 2; ++k) dst[n][k] = *(const LAS bf16x8*)(lds + PG8_SB(b, h) + boff + n * 2048 + k * 1024); } while (0)
; #define PG8_MMA(ai, bj, At, Bt) do { __builtin_amdgcn_s_setprio(1); _Pragma("unroll") for (int m = 0; m < 4; ++m) _Pragma("unroll") for (int n = 0; n < 2; ++n) _Pragma("unroll") for (int k = 0; k < 2; ++k) \
;         acc[ai][bj][m][n] = __builtin_amdgcn_mfma_f32_16x16x32_bf16(Bt[n][k], At[m][k], acc[ai][bj][m][n], 0, 0, 0); __builtin_amdgcn_s_setprio(0); } while (0)
; #define PG8_WAIT_V(n) asm volatile("s_waitcnt vmcnt(" #n ")" ::: "memory")
; #define PG8_WAIT_L(n) asm volatile("s_waitcnt lgkmcnt(" #n ")" ::: "memory")
; #define PG8_BAR __builtin_amdgcn_s_barrier()
; #define PG8_SCHED __builtin_amdgcn_sched_barrier(0)
; __device__ __forceinline__ void gemm_phase(LAS unsigned char* lds, const Params& p, const Sched& S, float alpha, const int TIDX) {
;     ...
;         for (int t = 0; t < nt; t += 2) {
;             const bool last = (t == nt - 2);
;             const char* a1 = cA + (size_t)(t + 1) * kstep;
;             const char* a2 = last ? nA : cA + (size_t)(t + 2) * kstep; const char* b2 = last ? nB : cB + (size_t)(t + 2) * kstep;
;             const char* a3 = a2 + kstep; const char* b3 = b2 + kstep;
;             PG8_LDB(B0, 0, 0); PG8_SCHED; PG8_LDA(At, 0, 0); PG8_STAGE(PG8_SA(1, 1), a1 + hstep, voffA);
;             PG8_WAIT_L(8); PG8_BAR; PG8_WAIT_L(0); PG8_MMA(0, 0, At, B0); PG8_BAR; PG8_SCHED;
;             PG8_LDB(B1, 0, 1); PG8_STAGE(PG8_SB(0, 0), b2, voffB);
;             PG8_BAR; PG8_WAIT_L(0); PG8_MMA(0, 1, At, B1); PG8_BAR;
;     ...
;             PG8_BAR; PG8_WAIT_L(0); PG8_MMA(1, 0, At, B0); PG8_BAR; PG8_SCHED;
;             PG8_STAGE(PG8_SB(1, 1), b3 + hstep, voffB);
;             PG8_WAIT_V(6); PG8_BAR; PG8_MMA(1, 1, At, B1); PG8_BAR;
;         }
	s_waitcnt lgkmcnt(0)
	s_waitcnt lgkmcnt(0)
	v_mfma_f32_16x16x32_bf16 v[62:65], v[130:133], v[162:165], v[62:65]
	v_mfma_f32_16x16x32_bf16 v[54:57], v[154:157], v[162:165], v[54:57]
	v_mfma_f32_16x16x32_bf16 v[46:49], v[130:133], v[174:177], v[46:49]
	v_mfma_f32_16x16x32_bf16 v[38:41], v[154:157], v[174:177], v[38:41]
	v_mfma_f32_16x16x32_bf16 v[30:33], v[130:133], v[182:185], v[30:33]
	v_mfma_f32_16x16x32_bf16 v[22:25], v[154:157], v[182:185], v[22:25]
	v_mfma_f32_16x16x32_bf16 v[14:17], v[130:133], v[208:211], v[14:17]
	v_mfma_f32_16x16x32_bf16 v[6:9], v[154:157], v[208:211], v[6:9]
	v_mfma_f32_16x16x32_bf16 v[62:65], v[134:137], v[170:173], v[62:65]
	v_mfma_f32_16x16x32_bf16 v[54:57], v[158:161], v[170:173], v[54:57]
	v_mfma_f32_16x16x32_bf16 v[46:49], v[134:137], v[178:181], v[46:49]
	v_mfma_f32_16x16x32_bf16 v[38:41], v[158:161], v[178:181], v[38:41]
	v_mfma_f32_16x16x32_bf16 v[30:33], v[134:137], v[204:207], v[30:33]
	v_mfma_f32_16x16x32_bf16 v[22:25], v[158:161], v[204:207], v[22:25]
	v_mfma_f32_16x16x32_bf16 v[14:17], v[134:137], v[212:215], v[14:17]
	v_mfma_f32_16x16x32_bf16 v[6:9], v[158:161], v[212:215], v[6:9]
	s_barrier
	s_add_i32 s48, s48, s34
	v_lshl_add_u64 v[130:131], v[236:237], 0, s[88:89]
	s_mov_b32 m0, s48
	s_nop 0
	global_load_lds_dwordx4 v[130:131], off
	v_lshl_add_u64 v[130:131], v[238:239], 0, s[88:89]
	s_add_i32 m0, s48, 0x2000
	s_nop 0
	global_load_lds_dwordx4 v[130:131], off
	s_waitcnt vmcnt(6)
	s_barrier
	v_mfma_f32_16x16x32_bf16 v[58:61], v[216:219], v[162:165], v[58:61]
	v_mfma_f32_16x16x32_bf16 v[50:53], v[224:227], v[162:165], v[50:53]
	v_mfma_f32_16x16x32_bf16 v[42:45], v[216:219], v[174:177], v[42:45]
	v_mfma_f32_16x16x32_bf16 v[34:37], v[224:227], v[174:177], v[34:37]
	v_mfma_f32_16x16x32_bf16 v[26:29], v[216:219], v[182:185], v[26:29]
	v_mfma_f32_16x16x32_bf16 v[18:21], v[224:227], v[182:185], v[18:21]
	v_mfma_f32_16x16x32_bf16 v[10:13], v[216:219], v[208:211], v[10:13]
	v_mfma_f32_16x16x32_bf16 v[2:5], v[224:227], v[208:211], v[2:5]
	v_mfma_f32_16x16x32_bf16 v[58:61], v[220:223], v[170:173], v[58:61]
	v_mfma_f32_16x16x32_bf16 v[50:53], v[228:231], v[170:173], v[50:53]
	v_mfma_f32_16x16x32_bf16 v[42:45], v[220:223], v[178:181], v[42:45]
	v_mfma_f32_16x16x32_bf16 v[34:37], v[228:231], v[178:181], v[34:37]
	v_mfma_f32_16x16x32_bf16 v[26:29], v[220:223], v[204:207], v[26:29]
	v_mfma_f32_16x16x32_bf16 v[18:21], v[228:231], v[204:207], v[18:21]
	v_mfma_f32_16x16x32_bf16 v[10:13], v[220:223], v[212:215], v[10:13]
	v_mfma_f32_16x16x32_bf16 v[2:5], v[228:231], v[212:215], v[2:5]
	s_add_u32 s6, s6, 0x100
	s_addc_u32 s7, s7, 0
	s_add_u32 s39, s39, 0x100
	s_addc_u32 s56, s56, 0
	s_cmp_ge_i32 s57, s79
	s_mov_b32 s48, s57
	s_barrier
	s_cbranch_scc0 .LBB0_289
	s_branch .LBB0_291
.LBB0_289:
	s_add_i32 s57, s48, 2
	s_add_u32 s50, s6, 0x80
	s_addc_u32 s49, s7, 0
	s_add_i32 s74, 0, 0x10000
	v_add_u32_e32 v0, s74, v200
	ds_read_b128 v[130:133], v0
	ds_read_b128 v[134:137], v0 offset:1024
	ds_read_b128 v[154:157], v0 offset:2048
	ds_read_b128 v[158:161], v0 offset:3072
	s_cmp_eq_u32 s38, s48
	s_cselect_b32 s48, s44, s50
	s_cselect_b32 s49, s45, s49
	s_cselect_b32 s51, s47, s56
	s_cselect_b32 s50, s46, s39
	v_lshl_add_u64 v[166:167], s[6:7], 0, v[150:151]
	s_add_i32 m0, s35, 0xc000
	ds_read_b128 v[162:165], v202
	ds_read_b128 v[170:173], v202 offset:1024
	ds_read_b128 v[174:177], v202 offset:2048
	ds_read_b128 v[178:181], v202 offset:3072
	ds_read_b128 v[182:185], v202 offset:4096
	ds_read_b128 v[204:207], v202 offset:5120
	ds_read_b128 v[208:211], v202 offset:6144
	ds_read_b128 v[212:215], v202 offset:7168
	global_load_lds_dwordx4 v[166:167], off
	v_lshl_add_u64 v[166:167], s[6:7], 0, v[152:153]
	s_add_i32 m0, s35, 0xe000
	s_nop 0
	global_load_lds_dwordx4 v[166:167], off
	s_waitcnt lgkmcnt(8)
	s_barrier
	s_waitcnt lgkmcnt(0)
	s_waitcnt lgkmcnt(0)
	v_mfma_f32_16x16x32_bf16 v[126:129], v[130:133], v[162:165], v[126:129]
	v_mfma_f32_16x16x32_bf16 v[118:121], v[154:157], v[162:165], v[118:121]
	v_mfma_f32_16x16x32_bf16 v[110:113], v[130:133], v[174:177], v[110:113]
	v_mfma_f32_16x16x32_bf16 v[102:105], v[154:157], v[174:177], v[102:105]
	v_mfma_f32_16x16x32_bf16 v[94:97], v[130:133], v[182:185], v[94:97]
	v_mfma_f32_16x16x32_bf16 v[86:89], v[154:157], v[182:185], v[86:89]
	v_mfma_f32_16x16x32_bf16 v[78:81], v[130:133], v[208:211], v[78:81]
	v_mfma_f32_16x16x32_bf16 v[70:73], v[154:157], v[208:211], v[70:73]
	v_mfma_f32_16x16x32_bf16 v[126:129], v[134:137], v[170:173], v[126:129]
	v_mfma_f32_16x16x32_bf16 v[118:121], v[158:161], v[170:173], v[118:121]
	v_mfma_f32_16x16x32_bf16 v[110:113], v[134:137], v[178:181], v[110:113]
	v_mfma_f32_16x16x32_bf16 v[102:105], v[158:161], v[178:181], v[102:105]
	v_mfma_f32_16x16x32_bf16 v[94:97], v[134:137], v[204:207], v[94:97]
	v_mfma_f32_16x16x32_bf16 v[86:89], v[158:161], v[204:207], v[86:89]
	v_mfma_f32_16x16x32_bf16 v[78:81], v[134:137], v[212:215], v[78:81]
	v_mfma_f32_16x16x32_bf16 v[70:73], v[158:161], v[212:215], v[70:73]
	s_barrier
	s_add_i32 s75, 0, 0x14000
	s_add_i32 s74, s74, s34
	v_add_u32_e32 v0, s75, v200
	v_lshl_add_u64 v[166:167], s[50:51], 0, v[140:141]
	s_mov_b32 m0, s74
	ds_read_b128 v[216:219], v0
	ds_read_b128 v[220:223], v0 offset:1024
	ds_read_b128 v[224:227], v0 offset:2048
	ds_read_b128 v[228:231], v0 offset:3072
	global_load_lds_dwordx4 v[166:167], off
	v_lshl_add_u64 v[186:187], s[50:51], 0, v[144:145]
	s_add_i32 m0, s74, 0x2000
	s_nop 0
	global_load_lds_dwordx4 v[186:187], off
	s_barrier
; #define PG8_STAGE(bufoff, gbase, voff) do { _Pragma("unroll") for (int _i = 0; _i < 2; ++_i) \
;         __builtin_amdgcn_global_load_lds((const unsigned*)((const char*)(gbase) + (voff)[_i]), (LAS unsigned*)(lds + (bufoff) + ldsw + _i * 8192), 16, 0, 0); } while (0)
; #define PG8_LDA(dst, b, h) do { _Pragma("unroll") for (int m = 0; m < 4; ++m) _Pragma("unroll") for (int k = 0; k < 2; ++k) dst[m][k] = *(const LAS bf16x8*)(lds + PG8_SA(b, h) + aoff + m * 2048 + k * 1024); } while (0)
; #define PG8_LDB(dst, b, h) do { _Pragma("unroll") for (int n = 0; n < 2; ++n) _Pragma("unroll") for (int k = 0; k < 2; ++k) dst[n][k] = *(const LAS bf16x8*)(lds + PG8_SB(b, h) + boff + n * 2048 + k * 1024); } while (0)
; #define PG8_MMA(ai, bj, At, Bt) do { __builtin_amdgcn_s_setprio(1); _Pragma("unroll") for (int m = 0; m < 4; ++m) _Pragma("unroll") for (int n = 0; n < 2; ++n) _Pragma("unroll") for (int k = 0; k < 2; ++k) \
;         acc[ai][bj][m][n] = __builtin_amdgcn_mfma_f32_16x16x32_bf16(Bt[n][k], At[m][k], acc[ai][bj][m][n], 0, 0, 0); __builtin_amdgcn_s_setprio(0); } while (0)
; #define PG8_WAIT_V(n) asm volatile("s_waitcnt vmcnt(" #n ")" ::: "memory")
; #define PG8_WAIT_L(n) asm volatile("s_waitcnt lgkmcnt(" #n ")" ::: "memory")
; #define PG8_BAR __builtin_amdgcn_s_barrier()
; #define PG8_SCHED __builtin_amdgcn_sched_barrier(0)
; __device__ __forceinline__ void gemm_phase(LAS unsigned char* lds, const Params& p, const Sched& S, float alpha, const int TIDX) {
;     ...
;             PG8_WAIT_L(8); PG8_BAR; PG8_WAIT_L(0); PG8_MMA(0, 0, At, B0); PG8_BAR; PG8_SCHED;
;             PG8_LDB(B1, 0, 1); PG8_STAGE(PG8_SB(0, 0), b2, voffB);
;             PG8_BAR; PG8_WAIT_L(0); PG8_MMA(0, 1, At, B1); PG8_BAR;
;             PG8_LDA(At, 0, 1); PG8_STAGE(PG8_SA(0, 0), a2, voffA);
;             PG8_BAR; PG8_WAIT_L(0); PG8_MMA(1, 0, At, B0); PG8_BAR; PG8_SCHED;
;             PG8_STAGE(PG8_SB(0, 1), b2 + hstep, voffB);
;             PG8_WAIT_V(6); PG8_BAR; PG8_MMA(1, 1, At, B1); PG8_BAR;
;             PG8_LDB(B0, 1, 0); PG8_SCHED; PG8_LDA(At, 1, 0); PG8_STAGE(PG8_SA(0, 1), a2 + hstep, voffA);
;             PG8_WAIT_L(8); PG8_BAR; PG8_WAIT_L(0); PG8_MMA(0, 0, At, B0); PG8_BAR; PG8_SCHED;
;             PG8_LDB(B1, 1, 1); PG8_STAGE(PG8_SB(1, 0), b3, voffB);
	s_waitcnt lgkmcnt(0)
	s_waitcnt lgkmcnt(0)
	v_mfma_f32_16x16x32_bf16 v[122:125], v[216:219], v[162:165], v[122:125]
	v_mfma_f32_16x16x32_bf16 v[114:117], v[224:227], v[162:165], v[114:117]
	v_mfma_f32_16x16x32_bf16 v[106:109], v[216:219], v[174:177], v[106:109]
	v_mfma_f32_16x16x32_bf16 v[98:101], v[224:227], v[174:177], v[98:101]
	v_mfma_f32_16x16x32_bf16 v[90:93], v[216:219], v[182:185], v[90:93]
	v_mfma_f32_16x16x32_bf16 v[82:85], v[224:227], v[182:185], v[82:85]
	v_mfma_f32_16x16x32_bf16 v[74:77], v[216:219], v[208:211], v[74:77]
	v_mfma_f32_16x16x32_bf16 v[66:69], v[224:227], v[208:211], v[66:69]
	v_mfma_f32_16x16x32_bf16 v[122:125], v[220:223], v[170:173], v[122:125]
	v_mfma_f32_16x16x32_bf16 v[114:117], v[228:231], v[170:173], v[114:117]
	v_mfma_f32_16x16x32_bf16 v[106:109], v[220:223], v[178:181], v[106:109]
	v_mfma_f32_16x16x32_bf16 v[98:101], v[228:231], v[178:181], v[98:101]
	v_mfma_f32_16x16x32_bf16 v[90:93], v[220:223], v[204:207], v[90:93]
	v_mfma_f32_16x16x32_bf16 v[82:85], v[228:231], v[204:207], v[82:85]
	v_mfma_f32_16x16x32_bf16 v[74:77], v[220:223], v[212:215], v[74:77]
	v_mfma_f32_16x16x32_bf16 v[66:69], v[228:231], v[212:215], v[66:69]
	s_mov_b32 m0, s35
	v_lshl_add_u64 v[232:233], s[48:49], 0, v[138:139]
	s_barrier
	ds_read_b128 v[162:165], v202 offset:16384
	ds_read_b128 v[170:173], v202 offset:17408
	ds_read_b128 v[174:177], v202 offset:18432
	ds_read_b128 v[178:181], v202 offset:19456
	ds_read_b128 v[182:185], v202 offset:20480
	ds_read_b128 v[204:207], v202 offset:21504
	ds_read_b128 v[208:211], v202 offset:22528
	ds_read_b128 v[212:215], v202 offset:23552
	global_load_lds_dwordx4 v[232:233], off
	v_lshl_add_u64 v[234:235], s[48:49], 0, v[142:143]
	s_mov_b32 m0, s36
	s_nop 0
	global_load_lds_dwordx4 v[234:235], off
	s_barrier
	s_waitcnt lgkmcnt(0)
	s_waitcnt lgkmcnt(0)
	v_mfma_f32_16x16x32_bf16 v[62:65], v[130:133], v[162:165], v[62:65]
	v_mfma_f32_16x16x32_bf16 v[54:57], v[154:157], v[162:165], v[54:57]
	v_mfma_f32_16x16x32_bf16 v[46:49], v[130:133], v[174:177], v[46:49]
	v_mfma_f32_16x16x32_bf16 v[38:41], v[154:157], v[174:177], v[38:41]
	v_mfma_f32_16x16x32_bf16 v[30:33], v[130:133], v[182:185], v[30:33]
	v_mfma_f32_16x16x32_bf16 v[22:25], v[154:157], v[182:185], v[22:25]
	v_mfma_f32_16x16x32_bf16 v[14:17], v[130:133], v[208:211], v[14:17]
	v_mfma_f32_16x16x32_bf16 v[6:9], v[154:157], v[208:211], v[6:9]
	v_mfma_f32_16x16x32_bf16 v[62:65], v[134:137], v[170:173], v[62:65]
	v_mfma_f32_16x16x32_bf16 v[54:57], v[158:161], v[170:173], v[54:57]
	v_mfma_f32_16x16x32_bf16 v[46:49], v[134:137], v[178:181], v[46:49]
	v_mfma_f32_16x16x32_bf16 v[38:41], v[158:161], v[178:181], v[38:41]
	v_mfma_f32_16x16x32_bf16 v[30:33], v[134:137], v[204:207], v[30:33]
	v_mfma_f32_16x16x32_bf16 v[22:25], v[158:161], v[204:207], v[22:25]
	v_mfma_f32_16x16x32_bf16 v[14:17], v[134:137], v[212:215], v[14:17]
	v_mfma_f32_16x16x32_bf16 v[6:9], v[158:161], v[212:215], v[6:9]
	s_barrier
	s_add_u32 s50, s50, s20
	s_addc_u32 s51, s51, 0
	s_add_i32 s74, s75, s34
	v_lshl_add_u64 v[236:237], s[50:51], 0, v[140:141]
	s_mov_b32 m0, s74
	v_lshl_add_u64 v[238:239], s[50:51], 0, v[144:145]
	global_load_lds_dwordx4 v[236:237], off
	s_add_i32 m0, s74, 0x2000
	s_nop 0
	global_load_lds_dwordx4 v[238:239], off
	s_waitcnt vmcnt(6)
	s_barrier
	v_mfma_f32_16x16x32_bf16 v[58:61], v[216:219], v[162:165], v[58:61]
	v_mfma_f32_16x16x32_bf16 v[50:53], v[224:227], v[162:165], v[50:53]
	v_mfma_f32_16x16x32_bf16 v[42:45], v[216:219], v[174:177], v[42:45]
	v_mfma_f32_16x16x32_bf16 v[34:37], v[224:227], v[174:177], v[34:37]
	v_mfma_f32_16x16x32_bf16 v[26:29], v[216:219], v[182:185], v[26:29]
	v_mfma_f32_16x16x32_bf16 v[18:21], v[224:227], v[182:185], v[18:21]
	v_mfma_f32_16x16x32_bf16 v[10:13], v[216:219], v[208:211], v[10:13]
	v_mfma_f32_16x16x32_bf16 v[2:5], v[224:227], v[208:211], v[2:5]
	v_mfma_f32_16x16x32_bf16 v[58:61], v[220:223], v[170:173], v[58:61]
	v_mfma_f32_16x16x32_bf16 v[50:53], v[228:231], v[170:173], v[50:53]
	v_mfma_f32_16x16x32_bf16 v[42:45], v[220:223], v[178:181], v[42:45]
	v_mfma_f32_16x16x32_bf16 v[34:37], v[228:231], v[178:181], v[34:37]
	v_mfma_f32_16x16x32_bf16 v[26:29], v[220:223], v[204:207], v[26:29]
	v_mfma_f32_16x16x32_bf16 v[18:21], v[228:231], v[204:207], v[18:21]
	v_mfma_f32_16x16x32_bf16 v[10:13], v[220:223], v[212:215], v[10:13]
	v_mfma_f32_16x16x32_bf16 v[2:5], v[228:231], v[212:215], v[2:5]
	s_add_i32 s50, 0, 0x18000
	v_add_u32_e32 v0, s50, v200
	s_barrier
	ds_read_b128 v[130:133], v0
	ds_read_b128 v[134:137], v0 offset:1024
	ds_read_b128 v[154:157], v0 offset:2048
	ds_read_b128 v[158:161], v0 offset:3072
	s_add_u32 s48, s48, s20
	s_addc_u32 s49, s49, 0
	s_mov_b32 m0, s37
	v_lshl_add_u64 v[216:217], s[48:49], 0, v[138:139]
	ds_read_b128 v[162:165], v202 offset:32768
	ds_read_b128 v[170:173], v202 offset:33792
	ds_read_b128 v[174:177], v202 offset:34816
	ds_read_b128 v[178:181], v202 offset:35840
	ds_read_b128 v[182:185], v202 offset:36864
	ds_read_b128 v[204:207], v202 offset:37888
	ds_read_b128 v[208:211], v202 offset:38912
	ds_read_b128 v[212:215], v202 offset:39936
	global_load_lds_dwordx4 v[216:217], off
	v_lshl_add_u64 v[216:217], s[48:49], 0, v[142:143]
	s_mov_b32 m0, s24
	s_nop 0
	global_load_lds_dwordx4 v[216:217], off
	s_waitcnt lgkmcnt(8)
	s_barrier
; #define PG8_STAGE(bufoff, gbase, voff) do { _Pragma("unroll") for (int _i = 0; _i < 2; ++_i) \
;         __builtin_amdgcn_global_load_lds((const unsigned*)((const char*)(gbase) + (voff)[_i]), (LAS unsigned*)(lds + (bufoff) + ldsw + _i * 8192), 16, 0, 0); } while (0)
; #define PG8_LDA(dst, b, h) do { _Pragma("unroll") for (int m = 0; m < 4; ++m) _Pragma("unroll") for (int k = 0; k < 2; ++k) dst[m][k] = *(const LAS bf16x8*)(lds + PG8_SA(b, h) + aoff + m * 2048 + k * 1024); } while (0)
; #define PG8_LDB(dst, b, h) do { _Pragma("unroll") for (int n = 0; n < 2; ++n) _Pragma("unroll") for (int k = 0; k < 2; ++k) dst[n][k] = *(const LAS bf16x8*)(lds + PG8_SB(b, h) + boff + n * 2048 + k * 1024); } while (0)
; #define PG8_MMA(ai, bj, At, Bt) do { __builtin_amdgcn_s_setprio(1); _Pragma("unroll") for (int m = 0; m < 4; ++m) _Pragma("unroll") for (int n = 0; n < 2; ++n) _Pragma("unroll") for (int k = 0; k < 2; ++k) \
;         acc[ai][bj][m][n] = __builtin_amdgcn_mfma_f32_16x16x32_bf16(Bt[n][k], At[m][k], acc[ai][bj][m][n], 0, 0, 0); __builtin_amdgcn_s_setprio(0); } while (0)
; #define PG8_WAIT_V(n) asm volatile("s_waitcnt vmcnt(" #n ")" ::: "memory")
; #define PG8_WAIT_L(n) asm volatile("s_waitcnt lgkmcnt(" #n ")" ::: "memory")
; #define PG8_BAR __builtin_amdgcn_s_barrier()
; #define PG8_SCHED __builtin_amdgcn_sched_barrier(0)
; __device__ __forceinline__ void gemm_phase(LAS unsigned char* lds, const Params& p, const Sched& S, float alpha, const int TIDX) {
;     ...
;             PG8_WAIT_L(8); PG8_BAR; PG8_WAIT_L(0); PG8_MMA(0, 0, At, B0); PG8_BAR; PG8_SCHED;
;             PG8_LDB(B1, 1, 1); PG8_STAGE(PG8_SB(1, 0), b3, voffB);
;             PG8_BAR; PG8_WAIT_L(0); PG8_MMA(0, 1, At, B1); PG8_BAR;
;             PG8_LDA(At, 1, 1); PG8_STAGE(PG8_SA(1, 0), a3, voffA);
;             PG8_BAR; PG8_WAIT_L(0); PG8_MMA(1, 0, At, B0); PG8_BAR; PG8_SCHED;
;             PG8_STAGE(PG8_SB(1, 1), b3 + hstep, voffB);
;             PG8_WAIT_V(6); PG8_BAR; PG8_MMA(1, 1, At, B1); PG8_BAR;
;         }
	s_waitcnt lgkmcnt(0)
	s_waitcnt lgkmcnt(0)
	v_mfma_f32_16x16x32_bf16 v[126:129], v[130:133], v[162:165], v[126:129]
	v_mfma_f32_16x16x32_bf16 v[118:121], v[154:157], v[162:165], v[118:121]
	v_mfma_f32_16x16x32_bf16 v[110:113], v[130:133], v[174:177], v[110:113]
	v_mfma_f32_16x16x32_bf16 v[102:105], v[154:157], v[174:177], v[102:105]
	v_mfma_f32_16x16x32_bf16 v[94:97], v[130:133], v[182:185], v[94:97]
	v_mfma_f32_16x16x32_bf16 v[86:89], v[154:157], v[182:185], v[86:89]
	v_mfma_f32_16x16x32_bf16 v[78:81], v[130:133], v[208:211], v[78:81]
	v_mfma_f32_16x16x32_bf16 v[70:73], v[154:157], v[208:211], v[70:73]
	v_mfma_f32_16x16x32_bf16 v[126:129], v[134:137], v[170:173], v[126:129]
	v_mfma_f32_16x16x32_bf16 v[118:121], v[158:161], v[170:173], v[118:121]
	v_mfma_f32_16x16x32_bf16 v[110:113], v[134:137], v[178:181], v[110:113]
	v_mfma_f32_16x16x32_bf16 v[102:105], v[158:161], v[178:181], v[102:105]
	v_mfma_f32_16x16x32_bf16 v[94:97], v[134:137], v[204:207], v[94:97]
	v_mfma_f32_16x16x32_bf16 v[86:89], v[158:161], v[204:207], v[86:89]
	v_mfma_f32_16x16x32_bf16 v[78:81], v[134:137], v[212:215], v[78:81]
	v_mfma_f32_16x16x32_bf16 v[70:73], v[158:161], v[212:215], v[70:73]
	s_barrier
	s_add_i32 s48, 0, 0x1c000
	s_add_i32 s49, s50, s34
	v_add_u32_e32 v0, s48, v200
	v_lshl_add_u64 v[166:167], v[166:167], 0, s[88:89]
	s_mov_b32 m0, s49
	ds_read_b128 v[216:219], v0
	ds_read_b128 v[220:223], v0 offset:1024
	ds_read_b128 v[224:227], v0 offset:2048
	ds_read_b128 v[228:231], v0 offset:3072
	global_load_lds_dwordx4 v[166:167], off
	v_lshl_add_u64 v[166:167], v[186:187], 0, s[88:89]
	s_add_i32 m0, s49, 0x2000
	s_nop 0
	global_load_lds_dwordx4 v[166:167], off
	s_barrier
	s_waitcnt lgkmcnt(0)
	s_waitcnt lgkmcnt(0)
	v_mfma_f32_16x16x32_bf16 v[122:125], v[216:219], v[162:165], v[122:125]
	v_mfma_f32_16x16x32_bf16 v[114:117], v[224:227], v[162:165], v[114:117]
	v_mfma_f32_16x16x32_bf16 v[106:109], v[216:219], v[174:177], v[106:109]
	v_mfma_f32_16x16x32_bf16 v[98:101], v[224:227], v[174:177], v[98:101]
	v_mfma_f32_16x16x32_bf16 v[90:93], v[216:219], v[182:185], v[90:93]
	v_mfma_f32_16x16x32_bf16 v[82:85], v[224:227], v[182:185], v[82:85]
	v_mfma_f32_16x16x32_bf16 v[74:77], v[216:219], v[208:211], v[74:77]
	v_mfma_f32_16x16x32_bf16 v[66:69], v[224:227], v[208:211], v[66:69]
	v_mfma_f32_16x16x32_bf16 v[122:125], v[220:223], v[170:173], v[122:125]
	v_mfma_f32_16x16x32_bf16 v[114:117], v[228:231], v[170:173], v[114:117]
	v_mfma_f32_16x16x32_bf16 v[106:109], v[220:223], v[178:181], v[106:109]
	v_mfma_f32_16x16x32_bf16 v[98:101], v[228:231], v[178:181], v[98:101]
	v_mfma_f32_16x16x32_bf16 v[90:93], v[220:223], v[204:207], v[90:93]
	v_mfma_f32_16x16x32_bf16 v[82:85], v[228:231], v[204:207], v[82:85]
	v_mfma_f32_16x16x32_bf16 v[74:77], v[220:223], v[212:215], v[74:77]
	v_mfma_f32_16x16x32_bf16 v[66:69], v[228:231], v[212:215], v[66:69]
	s_mov_b32 m0, s25
	v_lshl_add_u64 v[166:167], v[232:233], 0, s[88:89]
	s_barrier
	ds_read_b128 v[162:165], v202 offset:49152
	ds_read_b128 v[170:173], v202 offset:50176
	ds_read_b128 v[174:177], v202 offset:51200
	ds_read_b128 v[178:181], v202 offset:52224
	ds_read_b128 v[182:185], v202 offset:53248
	ds_read_b128 v[204:207], v202 offset:54272
	ds_read_b128 v[208:211], v202 offset:55296
	ds_read_b128 v[212:215], v202 offset:56320
	global_load_lds_dwordx4 v[166:167], off
	v_lshl_add_u64 v[166:167], v[234:235], 0, s[88:89]
	s_mov_b32 m0, s68
	s_nop 0
	global_load_lds_dwordx4 v[166:167], off
	s_barrier
	s_waitcnt lgkmcnt(0)
	s_waitcnt lgkmcnt(0)
	v_mfma_f32_16x16x32_bf16 v[62:65], v[130:133], v[162:165], v[62:65]
	v_mfma_f32_16x16x32_bf16 v[54:57], v[154:157], v[162:165], v[54:57]
	v_mfma_f32_16x16x32_bf16 v[46:49], v[130:133], v[174:177], v[46:49]
	v_mfma_f32_16x16x32_bf16 v[38:41], v[154:157], v[174:177], v[38:41]
	v_mfma_f32_16x16x32_bf16 v[30:33], v[130:133], v[182:185], v[30:33]
	v_mfma_f32_16x16x32_bf16 v[22:25], v[154:157], v[182:185], v[22:25]
	v_mfma_f32_16x16x32_bf16 v[14:17], v[130:133], v[208:211], v[14:17]
	v_mfma_f32_16x16x32_bf16 v[6:9], v[154:157], v[208:211], v[6:9]
	v_mfma_f32_16x16x32_bf16 v[62:65], v[134:137], v[170:173], v[62:65]
	v_mfma_f32_16x16x32_bf16 v[54:57], v[158:161], v[170:173], v[54:57]
	v_mfma_f32_16x16x32_bf16 v[46:49], v[134:137], v[178:181], v[46:49]
	v_mfma_f32_16x16x32_bf16 v[38:41], v[158:161], v[178:181], v[38:41]
	v_mfma_f32_16x16x32_bf16 v[30:33], v[134:137], v[204:207], v[30:33]
	v_mfma_f32_16x16x32_bf16 v[22:25], v[158:161], v[204:207], v[22:25]
	v_mfma_f32_16x16x32_bf16 v[14:17], v[134:137], v[212:215], v[14:17]
	v_mfma_f32_16x16x32_bf16 v[6:9], v[158:161], v[212:215], v[6:9]
	s_barrier
	s_add_i32 s48, s48, s34
	v_lshl_add_u64 v[130:131], v[236:237], 0, s[88:89]
	s_mov_b32 m0, s48
	s_nop 0
	global_load_lds_dwordx4 v[130:131], off
	v_lshl_add_u64 v[130:131], v[238:239], 0, s[88:89]
	s_add_i32 m0, s48, 0x2000
	s_nop 0
	global_load_lds_dwordx4 v[130:131], off
	s_waitcnt vmcnt(6)
	s_barrier
	v_mfma_f32_16x16x32_bf16 v[58:61], v[216:219], v[162:165], v[58:61]
	v_mfma_f32_16x16x32_bf16 v[50:53], v[224:227], v[162:165], v[50:53]
	v_mfma_f32_16x16x32_bf16 v[42:45], v[216:219], v[174:177], v[42:45]
	v_mfma_f32_16x16x32_bf16 v[34:37], v[224:227], v[174:177], v[34:37]
	v_mfma_f32_16x16x32_bf16 v[26:29], v[216:219], v[182:185], v[26:29]
	v_mfma_f32_16x16x32_bf16 v[18:21], v[224:227], v[182:185], v[18:21]
	v_mfma_f32_16x16x32_bf16 v[10:13], v[216:219], v[208:211], v[10:13]
	v_mfma_f32_16x16x32_bf16 v[2:5], v[224:227], v[208:211], v[2:5]
	v_mfma_f32_16x16x32_bf16 v[58:61], v[220:223], v[170:173], v[58:61]
	v_mfma_f32_16x16x32_bf16 v[50:53], v[228:231], v[170:173], v[50:53]
	v_mfma_f32_16x16x32_bf16 v[42:45], v[220:223], v[178:181], v[42:45]
	v_mfma_f32_16x16x32_bf16 v[34:37], v[228:231], v[178:181], v[34:37]
	v_mfma_f32_16x16x32_bf16 v[26:29], v[220:223], v[204:207], v[26:29]
	v_mfma_f32_16x16x32_bf16 v[18:21], v[228:231], v[204:207], v[18:21]
	v_mfma_f32_16x16x32_bf16 v[10:13], v[220:223], v[212:215], v[10:13]
	v_mfma_f32_16x16x32_bf16 v[2:5], v[228:231], v[212:215], v[2:5]
	s_add_u32 s6, s6, 0x100
	s_addc_u32 s7, s7, 0
	s_add_u32 s39, s39, 0x100
	s_addc_u32 s56, s56, 0
	s_cmp_ge_i32 s57, s79
	s_mov_b32 s48, s57
	s_barrier
	s_cbranch_scc0 .LBB0_289
	s_branch .LBB0_291

; #define PG8_WAIT_V(n) asm volatile("s_waitcnt vmcnt(" #n ")" ::: "memory")
; #define PG8_BAR __builtin_amdgcn_s_barrier()
; __device__ __forceinline__ void gemm_phase(LAS unsigned char* lds, const Params& p, const Sched& S, float alpha, const int TIDX) {
;     ...
;     PG8_WAIT_V(0);
;     if (wr == 0) PG8_BAR;
;     PG8_BAR;
.LBB0_397:
	s_setprio 0
	s_waitcnt vmcnt(0)
	v_readlane_b32 s0, v255, 36
	s_cmpk_gt_u32 s0, 0xff
	s_movk_i32 s81, 0x3fff
	v_readlane_b32 s83, v254, 20
	s_movk_i32 s84, 0x2100
	s_mov_b32 s27, 0x8000
	s_mov_b32 s29, 0xc000
	s_mov_b32 s30, 0x10000
	s_mov_b32 s31, 0x18000
	s_mov_b32 s34, 0x1c000
	s_mov_b32 s35, 0x20000
	s_mov_b32 s44, 0x24000
	s_mov_b32 s45, 0x2c000
	s_mov_b32 s24, 0x44000
	s_mov_b32 s25, 0x48000
	s_mov_b32 s40, 0x4c000
	s_mov_b32 s41, 0x54000
	s_mov_b32 s46, 0x58000
	s_mov_b32 s47, 0x5c000
	s_cbranch_scc1 .LBB0_399
	s_barrier
